# attention steps: the remaining +0.0 row-sum adds and lane-exchange canonicalisation pairs removed (2 more VALU ops per key tile per wave)
# speedup vs baseline: 1.0035x; 1.0015x over previous
.LBB0_498:
	v_add_u32_e32 v208, s6, v220
	ds_read_b64_tr_b16 v[194:195], v208 offset:24576
	ds_read_b64_tr_b16 v[196:197], v208 offset:25088
	s_waitcnt lgkmcnt(9)
	v_mfma_f32_32x32x16_bf16 v[114:129], v[190:193], v[150:153], v[50:65]
	v_add_f32_e32 v98, v82, v83
	v_add_f32_e32 v98, v84, v98
	v_add_f32_e32 v98, v85, v98
	v_add_f32_e32 v98, v86, v98
	v_add_f32_e32 v98, v87, v98
	v_cvt_pk_bf16_f32 v158, v82, v83
	v_cvt_pk_bf16_f32 v159, v84, v85
	ds_read_b64_tr_b16 v[190:191], v208 offset:28672
	ds_read_b64_tr_b16 v[192:193], v208 offset:29184
	v_add_f32_e32 v82, v88, v98
	s_waitcnt lgkmcnt(10)
	v_mfma_f32_32x32x16_bf16 v[98:113], v[186:189], v[150:153], v[50:65]
	v_add_f32_e32 v82, v89, v82
	v_add_f32_e32 v82, v90, v82
	v_add_f32_e32 v82, v91, v82
	v_cvt_pk_bf16_f32 v160, v86, v87
	v_cvt_pk_bf16_f32 v161, v88, v89
	ds_read_b64_tr_b16 v[186:187], v208 offset:25600
	ds_read_b64_tr_b16 v[188:189], v208 offset:26112
	s_waitcnt lgkmcnt(11)
	v_mfma_f32_32x32x16_bf16 v[114:129], v[182:185], v[142:145], v[114:129]
	v_add_f32_e32 v82, v92, v82
	v_add_f32_e32 v82, v93, v82
	v_add_f32_e32 v82, v94, v82
	v_add_f32_e32 v82, v95, v82
	v_cvt_pk_bf16_f32 v154, v90, v91
	v_cvt_pk_bf16_f32 v155, v92, v93
	ds_read_b64_tr_b16 v[90:91], v208 offset:29696
	ds_read_b64_tr_b16 v[92:93], v208 offset:30208
	s_waitcnt lgkmcnt(12)
	v_mfma_f32_32x32x16_bf16 v[98:113], v[178:181], v[142:145], v[98:113]
	v_add_f32_e32 v82, v96, v82
	v_add_f32_e32 v82, v97, v82
	v_add_f32_e32 v82, v66, v82
	v_add_f32_e32 v82, v67, v82
	v_cvt_pk_bf16_f32 v156, v94, v95
	v_cvt_pk_bf16_f32 v157, v96, v97
	ds_read_b64_tr_b16 v[86:87], v208 offset:26624
	ds_read_b64_tr_b16 v[88:89], v208 offset:27136
	s_waitcnt lgkmcnt(13)
	v_mfma_f32_32x32x16_bf16 v[114:129], v[174:177], v[134:137], v[114:129]
	v_add_f32_e32 v82, v68, v82
	v_add_f32_e32 v82, v69, v82
	v_add_f32_e32 v82, v70, v82
	v_add_f32_e32 v94, v71, v82
	v_cvt_pk_bf16_f32 v146, v66, v67
	v_cvt_pk_bf16_f32 v147, v68, v69
	ds_read_b64_tr_b16 v[82:83], v208 offset:30720
	ds_read_b64_tr_b16 v[84:85], v208 offset:31232
	s_waitcnt lgkmcnt(14)
	v_mfma_f32_32x32x16_bf16 v[98:113], v[170:173], v[134:137], v[98:113]
	v_add_f32_e32 v66, v72, v94
	v_add_f32_e32 v66, v73, v66
	v_add_f32_e32 v66, v74, v66
	v_add_f32_e32 v66, v75, v66
	v_cvt_pk_bf16_f32 v148, v70, v71
	v_cvt_pk_bf16_f32 v149, v72, v73
	ds_read_b64_tr_b16 v[70:71], v208 offset:27648
	ds_read_b64_tr_b16 v[72:73], v208 offset:28160
	s_waitcnt lgkmcnt(14)
	v_mfma_f32_32x32x16_bf16 v[114:129], v[166:169], v[130:133], v[114:129]
	v_add_f32_e32 v66, v76, v66
	v_add_f32_e32 v66, v77, v66
	v_add_f32_e32 v66, v78, v66
	v_add_f32_e32 v94, v79, v66
	v_cvt_pk_bf16_f32 v138, v74, v75
	v_cvt_pk_bf16_f32 v139, v76, v77
	ds_read_b64_tr_b16 v[66:67], v208 offset:31744
	ds_read_b64_tr_b16 v[68:69], v208 offset:32256
	v_mfma_f32_32x32x16_bf16 v[98:113], v[162:165], v[130:133], v[98:113]
	v_add_f32_e32 v74, v80, v94
	v_add_f32_e32 v76, v81, v74
	s_nop 0
	v_cvt_pk_bf16_f32 v140, v78, v79
	v_cvt_pk_bf16_f32 v141, v80, v81
	v_lshl_add_u64 v[74:75], v[204:205], 0, s[68:69]
	s_add_i32 s3, s12, s49
	s_mov_b32 s6, m0
	s_mov_b32 m0, s3
	s_nop 0
	global_load_lds_dwordx4 v[74:75], off
	s_mov_b32 m0, s6
	v_lshl_add_u64 v[74:75], v[202:203], 0, s[68:69]
	s_add_i32 s3, s63, s61
	s_mov_b32 s6, m0
	s_mov_b32 m0, s3
	s_nop 0
	global_load_lds_dwordx4 v[74:75], off
	s_mov_b32 m0, s6
	s_nop 0
	s_nop 0
	v_max_f32_e32 v74, v114, v115
	v_max3_f32 v75, v116, v117, v99
	v_max3_f32 v74, v74, v98, v100
	v_max3_f32 v74, v74, v101, v118
	v_max3_f32 v75, v75, v120, v121
	v_max3_f32 v74, v74, v119, v102
	v_max3_f32 v75, v75, v104, v105
	v_max3_f32 v74, v74, v103, v122
	v_max3_f32 v75, v75, v124, v125
	v_max3_f32 v74, v74, v123, v106
	v_max3_f32 v75, v75, v108, v109
	v_max3_f32 v74, v74, v107, v126
	v_max3_f32 v75, v75, v128, v129
	v_max3_f32 v74, v74, v127, v110
	v_max3_f32 v75, v75, v112, v113
	v_max3_f32 v74, v74, v111, v75
	v_mov_b32_e32 v75, v74
	s_nop 1
	v_permlane32_swap_b32_e32 v74, v75
	s_nop 0
	s_nop 0
	v_max_f32_e32 v74, v74, v75
	v_cmp_lt_f32_e32 vcc, s33, v74
	s_cmp_lg_u64 vcc, 0
	v_add_f32_e32 v208, v222, v76
	s_cselect_b64 s[6:7], -1, 0
	s_cbranch_vccnz .LBB0_506

.LBB0_501:
	s_add_i32 s3, s63, 0x2000
	s_cmpk_lg_i32 s63, 0x4000
	s_cselect_b32 s62, s3, 0
	v_add_u32_e32 v210, s12, v220
	ds_read_b64_tr_b16 v[170:171], v210 offset:24576
	ds_read_b64_tr_b16 v[172:173], v210 offset:25088
	s_waitcnt lgkmcnt(9)
	v_mfma_f32_32x32x16_bf16 v[82:97], v[74:77], v[150:153], v[50:65]
	v_add_f32_e32 v66, v114, v115
	v_add_f32_e32 v66, v116, v66
	v_add_f32_e32 v66, v117, v66
	v_add_f32_e32 v66, v118, v66
	v_add_f32_e32 v66, v119, v66
	v_cvt_pk_bf16_f32 v158, v114, v115
	v_cvt_pk_bf16_f32 v159, v116, v117
	ds_read_b64_tr_b16 v[166:167], v210 offset:28672
	ds_read_b64_tr_b16 v[168:169], v210 offset:29184
	v_add_f32_e32 v66, v120, v66
	v_add_f32_e32 v66, v121, v66
	v_add_f32_e32 v66, v122, v66
	v_add_f32_e32 v114, v123, v66
	s_waitcnt lgkmcnt(10)
	v_mfma_f32_32x32x16_bf16 v[66:81], v[162:165], v[150:153], v[50:65]
	v_cvt_pk_bf16_f32 v160, v118, v119
	v_cvt_pk_bf16_f32 v161, v120, v121
	ds_read_b64_tr_b16 v[162:163], v210 offset:25600
	ds_read_b64_tr_b16 v[164:165], v210 offset:26112
	s_waitcnt lgkmcnt(11)
	v_mfma_f32_32x32x16_bf16 v[82:97], v[194:197], v[142:145], v[82:97]
	v_add_f32_e32 v114, v124, v114
	v_add_f32_e32 v114, v125, v114
	v_add_f32_e32 v114, v126, v114
	v_add_f32_e32 v114, v127, v114
	v_cvt_pk_bf16_f32 v154, v122, v123
	v_cvt_pk_bf16_f32 v155, v124, v125
	ds_read_b64_tr_b16 v[122:123], v210 offset:29696
	ds_read_b64_tr_b16 v[124:125], v210 offset:30208
	s_waitcnt lgkmcnt(12)
	v_mfma_f32_32x32x16_bf16 v[66:81], v[186:189], v[142:145], v[66:81]
	v_add_f32_e32 v114, v128, v114
	v_add_f32_e32 v114, v129, v114
	v_add_f32_e32 v114, v98, v114
	v_add_f32_e32 v114, v99, v114
	v_cvt_pk_bf16_f32 v156, v126, v127
	v_cvt_pk_bf16_f32 v157, v128, v129
	ds_read_b64_tr_b16 v[118:119], v210 offset:26624
	ds_read_b64_tr_b16 v[120:121], v210 offset:27136
	s_waitcnt lgkmcnt(13)
	v_mfma_f32_32x32x16_bf16 v[82:97], v[190:193], v[134:137], v[82:97]
	v_add_f32_e32 v114, v100, v114
	v_add_f32_e32 v114, v101, v114
	v_add_f32_e32 v114, v102, v114
	v_add_f32_e32 v126, v103, v114
	v_cvt_pk_bf16_f32 v146, v98, v99
	v_cvt_pk_bf16_f32 v147, v100, v101
	ds_read_b64_tr_b16 v[114:115], v210 offset:30720
	ds_read_b64_tr_b16 v[116:117], v210 offset:31232
	s_waitcnt lgkmcnt(14)
	v_mfma_f32_32x32x16_bf16 v[66:81], v[178:181], v[134:137], v[66:81]
	v_add_f32_e32 v98, v104, v126
	v_add_f32_e32 v98, v105, v98
	v_add_f32_e32 v98, v106, v98
	v_add_f32_e32 v98, v107, v98
	v_cvt_pk_bf16_f32 v148, v102, v103
	v_cvt_pk_bf16_f32 v149, v104, v105
	ds_read_b64_tr_b16 v[102:103], v210 offset:27648
	ds_read_b64_tr_b16 v[104:105], v210 offset:28160
	s_waitcnt lgkmcnt(14)
	v_mfma_f32_32x32x16_bf16 v[82:97], v[182:185], v[130:133], v[82:97]
	v_add_f32_e32 v98, v108, v98
	v_add_f32_e32 v98, v109, v98
	v_add_f32_e32 v98, v110, v98
	v_add_f32_e32 v126, v111, v98
	v_cvt_pk_bf16_f32 v138, v106, v107
	v_cvt_pk_bf16_f32 v139, v108, v109
	ds_read_b64_tr_b16 v[98:99], v210 offset:31744
	ds_read_b64_tr_b16 v[100:101], v210 offset:32256
	v_mfma_f32_32x32x16_bf16 v[66:81], v[174:177], v[130:133], v[66:81]
	v_add_f32_e32 v106, v112, v126
	v_add_f32_e32 v106, v113, v106
	s_nop 0
	v_cvt_pk_bf16_f32 v140, v110, v111
	v_cvt_pk_bf16_f32 v141, v112, v113
	s_nop 0
	s_nop 0
	v_max_f32_e32 v107, v82, v83
	s_nop 3
	v_max3_f32 v108, v84, v85, v67
	v_max3_f32 v107, v107, v66, v68
	v_max3_f32 v107, v107, v69, v86
	v_max3_f32 v108, v108, v88, v89
	v_max3_f32 v107, v107, v87, v70
	v_max3_f32 v108, v108, v72, v73
	v_max3_f32 v107, v107, v71, v90
	v_max3_f32 v108, v108, v92, v93
	v_max3_f32 v107, v107, v91, v74
	v_max3_f32 v108, v108, v76, v77
	v_max3_f32 v107, v107, v75, v94
	v_max3_f32 v108, v108, v96, v97
	v_max3_f32 v107, v107, v95, v78
	v_max3_f32 v108, v108, v80, v81
	v_add_f32_e32 v222, v208, v106
	v_max3_f32 v106, v107, v79, v108
	v_mov_b32_e32 v107, v106
	s_nop 1
	v_permlane32_swap_b32_e32 v106, v107
	s_nop 0
	s_nop 0
	s_add_i32 s3, s63, s49
	s_mov_b32 s6, m0
	s_mov_b32 m0, s3
	s_nop 0
	global_load_lds_dwordx4 v[204:205], off
	s_mov_b32 m0, s6
	v_max_f32_e32 v106, v106, v107
	s_add_i32 s3, s62, s61
	s_mov_b32 s6, m0
	s_mov_b32 m0, s3
	s_nop 0
	global_load_lds_dwordx4 v[202:203], off
	s_mov_b32 m0, s6
	v_cmp_lt_f32_e32 vcc, s33, v106
	s_cmp_lg_u64 vcc, 0
	s_cselect_b64 s[6:7], -1, 0
	s_cbranch_vccnz .LBB0_509

.LBB0_514:
	v_add_u32_e32 v194, s66, v220
	ds_read_b64_tr_b16 v[126:127], v194 offset:24576
	ds_read_b64_tr_b16 v[128:129], v194 offset:25088
	v_add_f32_e32 v98, v82, v83
	v_add_f32_e32 v98, v84, v98
	v_add_f32_e32 v98, v85, v98
	v_add_f32_e32 v98, v86, v98
	v_add_f32_e32 v114, v87, v98
	s_waitcnt lgkmcnt(9)
	v_mfma_f32_32x32x16_bf16 v[98:113], v[190:193], v[150:153], v[50:65]
	v_cvt_pk_bf16_f32 v158, v82, v83
	v_cvt_pk_bf16_f32 v159, v84, v85
	ds_read_b64_tr_b16 v[122:123], v194 offset:28672
	ds_read_b64_tr_b16 v[124:125], v194 offset:29184
	s_waitcnt lgkmcnt(10)
	v_mfma_f32_32x32x16_bf16 v[50:65], v[186:189], v[150:153], v[50:65]
	v_add_f32_e32 v82, v88, v114
	v_add_f32_e32 v82, v89, v82
	v_add_f32_e32 v82, v90, v82
	v_add_f32_e32 v82, v91, v82
	v_cvt_pk_bf16_f32 v160, v86, v87
	v_cvt_pk_bf16_f32 v161, v88, v89
	ds_read_b64_tr_b16 v[118:119], v194 offset:25600
	ds_read_b64_tr_b16 v[120:121], v194 offset:26112
	s_waitcnt lgkmcnt(11)
	v_mfma_f32_32x32x16_bf16 v[98:113], v[182:185], v[142:145], v[98:113]
	v_add_f32_e32 v82, v92, v82
	v_add_f32_e32 v82, v93, v82
	v_add_f32_e32 v82, v94, v82
	v_add_f32_e32 v82, v95, v82
	v_cvt_pk_bf16_f32 v154, v90, v91
	v_cvt_pk_bf16_f32 v155, v92, v93
	ds_read_b64_tr_b16 v[114:115], v194 offset:29696
	ds_read_b64_tr_b16 v[116:117], v194 offset:30208
	s_waitcnt lgkmcnt(12)
	v_mfma_f32_32x32x16_bf16 v[50:65], v[178:181], v[142:145], v[50:65]
	v_add_f32_e32 v82, v96, v82
	v_add_f32_e32 v82, v97, v82
	v_add_f32_e32 v82, v66, v82
	v_add_f32_e32 v82, v67, v82
	v_cvt_pk_bf16_f32 v156, v94, v95
	v_cvt_pk_bf16_f32 v157, v96, v97
	ds_read_b64_tr_b16 v[94:95], v194 offset:26624
	ds_read_b64_tr_b16 v[96:97], v194 offset:27136
	s_waitcnt lgkmcnt(13)
	v_mfma_f32_32x32x16_bf16 v[98:113], v[174:177], v[134:137], v[98:113]
	v_add_f32_e32 v82, v68, v82
	v_add_f32_e32 v82, v69, v82
	v_add_f32_e32 v82, v70, v82
	v_add_f32_e32 v82, v71, v82
	v_cvt_pk_bf16_f32 v146, v66, v67
	v_cvt_pk_bf16_f32 v147, v68, v69
	ds_read_b64_tr_b16 v[90:91], v194 offset:30720
	ds_read_b64_tr_b16 v[92:93], v194 offset:31232
	s_waitcnt lgkmcnt(14)
	v_mfma_f32_32x32x16_bf16 v[50:65], v[170:173], v[134:137], v[50:65]
	v_add_f32_e32 v66, v72, v82
	v_add_f32_e32 v66, v73, v66
	v_add_f32_e32 v66, v74, v66
	v_add_f32_e32 v66, v75, v66
	v_cvt_pk_bf16_f32 v148, v70, v71
	v_cvt_pk_bf16_f32 v149, v72, v73
	ds_read_b64_tr_b16 v[86:87], v194 offset:27648
	ds_read_b64_tr_b16 v[88:89], v194 offset:28160
	s_waitcnt lgkmcnt(14)
	v_mfma_f32_32x32x16_bf16 v[98:113], v[166:169], v[130:133], v[98:113]
	v_add_f32_e32 v66, v76, v66
	v_add_f32_e32 v66, v77, v66
	v_add_f32_e32 v66, v78, v66
	v_add_f32_e32 v66, v79, v66
	v_cvt_pk_bf16_f32 v138, v74, v75
	v_cvt_pk_bf16_f32 v139, v76, v77
	ds_read_b64_tr_b16 v[82:83], v194 offset:31744
	ds_read_b64_tr_b16 v[84:85], v194 offset:32256
	v_mfma_f32_32x32x16_bf16 v[50:65], v[162:165], v[130:133], v[50:65]
	v_add_f32_e32 v66, v80, v66
	v_add_f32_e32 v66, v81, v66
	s_nop 0
	v_cvt_pk_bf16_f32 v140, v78, v79
	v_cvt_pk_bf16_f32 v141, v80, v81
	s_nop 0
	s_nop 0
	v_max_f32_e32 v67, v98, v99
	s_nop 3
	v_max3_f32 v68, v100, v101, v51
	v_max3_f32 v67, v67, v50, v52
	v_max3_f32 v67, v67, v53, v102
	v_max3_f32 v68, v68, v104, v105
	v_max3_f32 v67, v67, v103, v54
	v_max3_f32 v68, v68, v56, v57
	v_max3_f32 v67, v67, v55, v106
	v_max3_f32 v68, v68, v108, v109
	v_max3_f32 v67, v67, v107, v58
	v_max3_f32 v68, v68, v60, v61
	v_max3_f32 v67, v67, v59, v110
	v_max3_f32 v68, v68, v112, v113
	v_max3_f32 v67, v67, v111, v62
	v_max3_f32 v68, v68, v64, v65
	v_add_f32_e32 v130, v222, v66
	v_max3_f32 v66, v67, v63, v68
	v_mov_b32_e32 v67, v66
	s_nop 1
	v_permlane32_swap_b32_e32 v66, v67
	s_nop 0
	s_nop 0
	v_max_f32_e32 v66, v66, v67
	v_cmp_lt_f32_e32 vcc, s33, v66
	s_cmp_lg_u64 vcc, 0
	s_cselect_b64 s[0:1], -1, 0
	s_cbranch_vccnz .LBB0_565

.LBB0_521:
	v_add_u32_e32 v202, s63, v220
	ds_read_b64_tr_b16 v[198:199], v202 offset:24576
	ds_read_b64_tr_b16 v[200:201], v202 offset:25088
	s_waitcnt lgkmcnt(9)
	v_mfma_f32_32x32x16_bf16 v[114:129], v[190:193], v[150:153], v[50:65]
	v_add_f32_e32 v98, v82, v83
	v_add_f32_e32 v98, v84, v98
	v_add_f32_e32 v98, v85, v98
	v_add_f32_e32 v98, v86, v98
	v_add_f32_e32 v98, v87, v98
	v_cvt_pk_bf16_f32 v158, v82, v83
	v_cvt_pk_bf16_f32 v159, v84, v85
	ds_read_b64_tr_b16 v[190:191], v202 offset:28672
	ds_read_b64_tr_b16 v[192:193], v202 offset:29184
	v_add_f32_e32 v82, v88, v98
	s_waitcnt lgkmcnt(10)
	v_mfma_f32_32x32x16_bf16 v[98:113], v[186:189], v[150:153], v[50:65]
	v_add_f32_e32 v82, v89, v82
	v_add_f32_e32 v82, v90, v82
	v_add_f32_e32 v82, v91, v82
	v_cvt_pk_bf16_f32 v160, v86, v87
	v_cvt_pk_bf16_f32 v161, v88, v89
	ds_read_b64_tr_b16 v[194:195], v202 offset:25600
	ds_read_b64_tr_b16 v[196:197], v202 offset:26112
	s_waitcnt lgkmcnt(11)
	v_mfma_f32_32x32x16_bf16 v[114:129], v[182:185], v[142:145], v[114:129]
	v_add_f32_e32 v82, v92, v82
	v_add_f32_e32 v82, v93, v82
	v_add_f32_e32 v82, v94, v82
	v_add_f32_e32 v82, v95, v82
	v_cvt_pk_bf16_f32 v154, v90, v91
	v_cvt_pk_bf16_f32 v155, v92, v93
	ds_read_b64_tr_b16 v[90:91], v202 offset:29696
	ds_read_b64_tr_b16 v[92:93], v202 offset:30208
	s_waitcnt lgkmcnt(12)
	v_mfma_f32_32x32x16_bf16 v[98:113], v[178:181], v[142:145], v[98:113]
	v_add_f32_e32 v82, v96, v82
	v_add_f32_e32 v82, v97, v82
	v_add_f32_e32 v82, v66, v82
	v_add_f32_e32 v82, v67, v82
	v_cvt_pk_bf16_f32 v156, v94, v95
	v_cvt_pk_bf16_f32 v157, v96, v97
	ds_read_b64_tr_b16 v[86:87], v202 offset:26624
	ds_read_b64_tr_b16 v[88:89], v202 offset:27136
	s_waitcnt lgkmcnt(13)
	v_mfma_f32_32x32x16_bf16 v[114:129], v[174:177], v[134:137], v[114:129]
	v_add_f32_e32 v82, v68, v82
	v_add_f32_e32 v82, v69, v82
	v_add_f32_e32 v82, v70, v82
	v_add_f32_e32 v94, v71, v82
	v_cvt_pk_bf16_f32 v146, v66, v67
	v_cvt_pk_bf16_f32 v147, v68, v69
	ds_read_b64_tr_b16 v[82:83], v202 offset:30720
	ds_read_b64_tr_b16 v[84:85], v202 offset:31232
	s_waitcnt lgkmcnt(14)
	v_mfma_f32_32x32x16_bf16 v[98:113], v[170:173], v[134:137], v[98:113]
	v_add_f32_e32 v66, v72, v94
	v_add_f32_e32 v66, v73, v66
	v_add_f32_e32 v66, v74, v66
	v_add_f32_e32 v66, v75, v66
	v_cvt_pk_bf16_f32 v148, v70, v71
	v_cvt_pk_bf16_f32 v149, v72, v73
	ds_read_b64_tr_b16 v[70:71], v202 offset:27648
	ds_read_b64_tr_b16 v[72:73], v202 offset:28160
	s_waitcnt lgkmcnt(14)
	v_mfma_f32_32x32x16_bf16 v[114:129], v[166:169], v[130:133], v[114:129]
	v_add_f32_e32 v66, v76, v66
	v_add_f32_e32 v66, v77, v66
	v_add_f32_e32 v66, v78, v66
	v_add_f32_e32 v94, v79, v66
	v_cvt_pk_bf16_f32 v138, v74, v75
	v_cvt_pk_bf16_f32 v139, v76, v77
	ds_read_b64_tr_b16 v[66:67], v202 offset:31744
	ds_read_b64_tr_b16 v[68:69], v202 offset:32256
	v_mfma_f32_32x32x16_bf16 v[98:113], v[162:165], v[130:133], v[98:113]
	v_add_f32_e32 v74, v80, v94
	v_add_f32_e32 v74, v81, v74
	s_nop 0
	v_cvt_pk_bf16_f32 v140, v78, v79
	v_cvt_pk_bf16_f32 v141, v80, v81
	s_add_i32 s0, s8, 1
	s_cmp_ge_u32 s0, s48
	s_cselect_b64 s[72:73], -1, 0
	s_and_b64 vcc, exec, s[72:73]
	s_cbranch_vccnz .LBB0_523
	s_add_i32 s0, s62, s49
	v_lshl_add_u64 v[76:77], v[210:211], 0, s[68:69]
	s_mov_b32 s1, m0
	s_mov_b32 m0, s0
	s_nop 0
	global_load_lds_dwordx4 v[76:77], off
	s_mov_b32 m0, s1

.LBB0_528:
	v_add_u32_e32 v224, s62, v220
	ds_read_b64_tr_b16 v[202:203], v224 offset:24576
	ds_read_b64_tr_b16 v[204:205], v224 offset:25088
	s_waitcnt lgkmcnt(9)
	v_mfma_f32_32x32x16_bf16 v[82:97], v[190:193], v[150:153], v[50:65]
	v_add_f32_e32 v66, v114, v115
	v_add_f32_e32 v66, v116, v66
	v_add_f32_e32 v66, v117, v66
	v_add_f32_e32 v66, v118, v66
	v_add_f32_e32 v66, v119, v66
	v_cvt_pk_bf16_f32 v158, v114, v115
	v_cvt_pk_bf16_f32 v159, v116, v117
	ds_read_b64_tr_b16 v[198:199], v224 offset:28672
	ds_read_b64_tr_b16 v[200:201], v224 offset:29184
	v_add_f32_e32 v66, v120, v66
	v_add_f32_e32 v66, v121, v66
	v_add_f32_e32 v66, v122, v66
	v_add_f32_e32 v114, v123, v66
	s_waitcnt lgkmcnt(10)
	v_mfma_f32_32x32x16_bf16 v[66:81], v[186:189], v[150:153], v[50:65]
	v_cvt_pk_bf16_f32 v160, v118, v119
	v_cvt_pk_bf16_f32 v161, v120, v121
	ds_read_b64_tr_b16 v[194:195], v224 offset:25600
	ds_read_b64_tr_b16 v[196:197], v224 offset:26112
	s_waitcnt lgkmcnt(11)
	v_mfma_f32_32x32x16_bf16 v[82:97], v[182:185], v[142:145], v[82:97]
	v_add_f32_e32 v114, v124, v114
	v_add_f32_e32 v114, v125, v114
	v_add_f32_e32 v114, v126, v114
	v_add_f32_e32 v114, v127, v114
	v_cvt_pk_bf16_f32 v154, v122, v123
	v_cvt_pk_bf16_f32 v155, v124, v125
	ds_read_b64_tr_b16 v[122:123], v224 offset:29696
	ds_read_b64_tr_b16 v[124:125], v224 offset:30208
	s_waitcnt lgkmcnt(12)
	v_mfma_f32_32x32x16_bf16 v[66:81], v[178:181], v[142:145], v[66:81]
	v_add_f32_e32 v114, v128, v114
	v_add_f32_e32 v114, v129, v114
	v_add_f32_e32 v114, v98, v114
	v_add_f32_e32 v114, v99, v114
	v_cvt_pk_bf16_f32 v156, v126, v127
	v_cvt_pk_bf16_f32 v157, v128, v129
	ds_read_b64_tr_b16 v[118:119], v224 offset:26624
	ds_read_b64_tr_b16 v[120:121], v224 offset:27136
	s_waitcnt lgkmcnt(13)
	v_mfma_f32_32x32x16_bf16 v[82:97], v[174:177], v[134:137], v[82:97]
	v_add_f32_e32 v114, v100, v114
	v_add_f32_e32 v114, v101, v114
	v_add_f32_e32 v114, v102, v114
	v_add_f32_e32 v126, v103, v114
	v_cvt_pk_bf16_f32 v146, v98, v99
	v_cvt_pk_bf16_f32 v147, v100, v101
	ds_read_b64_tr_b16 v[114:115], v224 offset:30720
	ds_read_b64_tr_b16 v[116:117], v224 offset:31232
	s_waitcnt lgkmcnt(14)
	v_mfma_f32_32x32x16_bf16 v[66:81], v[170:173], v[134:137], v[66:81]
	v_add_f32_e32 v98, v104, v126
	v_add_f32_e32 v98, v105, v98
	v_add_f32_e32 v98, v106, v98
	v_add_f32_e32 v98, v107, v98
	v_cvt_pk_bf16_f32 v148, v102, v103
	v_cvt_pk_bf16_f32 v149, v104, v105
	ds_read_b64_tr_b16 v[102:103], v224 offset:27648
	ds_read_b64_tr_b16 v[104:105], v224 offset:28160
	s_waitcnt lgkmcnt(14)
	v_mfma_f32_32x32x16_bf16 v[82:97], v[166:169], v[130:133], v[82:97]
	v_add_f32_e32 v98, v108, v98
	v_add_f32_e32 v98, v109, v98
	v_add_f32_e32 v98, v110, v98
	v_add_f32_e32 v126, v111, v98
	v_cvt_pk_bf16_f32 v138, v106, v107
	v_cvt_pk_bf16_f32 v139, v108, v109
	ds_read_b64_tr_b16 v[98:99], v224 offset:31744
	ds_read_b64_tr_b16 v[100:101], v224 offset:32256
	v_mfma_f32_32x32x16_bf16 v[66:81], v[162:165], v[130:133], v[66:81]
	v_add_f32_e32 v106, v112, v126
	v_add_f32_e32 v106, v113, v106
	s_nop 0
	v_cvt_pk_bf16_f32 v140, v110, v111
	v_cvt_pk_bf16_f32 v141, v112, v113
	s_add_i32 s12, s8, 2
	s_cmp_ge_u32 s12, s48
	s_cselect_b64 s[74:75], -1, 0
	s_and_b64 vcc, exec, s[74:75]
	s_cbranch_vccnz .LBB0_530
	s_add_i32 s0, s66, s49
	s_mov_b32 s1, m0
	s_mov_b32 m0, s0
	s_nop 0
	global_load_lds_dwordx4 v[210:211], off
	s_mov_b32 m0, s1

.LBB0_1278:
	v_add_u32_e32 v199, s38, v219
	ds_read_b64_tr_b16 v[194:195], v199 offset:24576
	ds_read_b64_tr_b16 v[196:197], v199 offset:25088
	s_waitcnt lgkmcnt(9)
	v_mfma_f32_32x32x16_bf16 v[114:129], v[98:101], v[170:173], v[50:65]
	v_add_f32_e32 v102, v82, v83
	v_add_f32_e32 v102, v84, v102
	v_add_f32_e32 v102, v85, v102
	v_add_f32_e32 v102, v86, v102
	v_add_f32_e32 v102, v87, v102
	v_cvt_pk_bf16_f32 v174, v82, v83
	v_cvt_pk_bf16_f32 v175, v84, v85
	ds_read_b64_tr_b16 v[190:191], v199 offset:28672
	ds_read_b64_tr_b16 v[192:193], v199 offset:29184
	v_add_f32_e32 v82, v88, v102
	s_waitcnt lgkmcnt(10)
	v_mfma_f32_32x32x16_bf16 v[98:113], v[186:189], v[170:173], v[50:65]
	v_add_f32_e32 v82, v89, v82
	v_add_f32_e32 v82, v90, v82
	v_add_f32_e32 v82, v91, v82
	v_cvt_pk_bf16_f32 v176, v86, v87
	v_cvt_pk_bf16_f32 v177, v88, v89
	ds_read_b64_tr_b16 v[186:187], v199 offset:25600
	ds_read_b64_tr_b16 v[188:189], v199 offset:26112
	s_waitcnt lgkmcnt(11)
	v_mfma_f32_32x32x16_bf16 v[114:129], v[182:185], v[162:165], v[114:129]
	v_add_f32_e32 v82, v92, v82
	v_add_f32_e32 v82, v93, v82
	v_add_f32_e32 v82, v94, v82
	v_add_f32_e32 v82, v95, v82
	v_cvt_pk_bf16_f32 v166, v90, v91
	v_cvt_pk_bf16_f32 v167, v92, v93
	ds_read_b64_tr_b16 v[90:91], v199 offset:29696
	ds_read_b64_tr_b16 v[92:93], v199 offset:30208
	s_waitcnt lgkmcnt(12)
	v_mfma_f32_32x32x16_bf16 v[98:113], v[178:181], v[162:165], v[98:113]
	v_add_f32_e32 v82, v96, v82
	v_add_f32_e32 v82, v97, v82
	v_add_f32_e32 v82, v66, v82
	v_add_f32_e32 v82, v67, v82
	v_cvt_pk_bf16_f32 v168, v94, v95
	v_cvt_pk_bf16_f32 v169, v96, v97
	ds_read_b64_tr_b16 v[86:87], v199 offset:26624
	ds_read_b64_tr_b16 v[88:89], v199 offset:27136
	s_waitcnt lgkmcnt(13)
	v_mfma_f32_32x32x16_bf16 v[114:129], v[142:145], v[154:157], v[114:129]
	v_add_f32_e32 v82, v68, v82
	v_add_f32_e32 v82, v69, v82
	v_add_f32_e32 v82, v70, v82
	v_add_f32_e32 v94, v71, v82
	v_cvt_pk_bf16_f32 v158, v66, v67
	v_cvt_pk_bf16_f32 v159, v68, v69
	ds_read_b64_tr_b16 v[82:83], v199 offset:30720
	ds_read_b64_tr_b16 v[84:85], v199 offset:31232
	s_waitcnt lgkmcnt(14)
	v_mfma_f32_32x32x16_bf16 v[98:113], v[138:141], v[154:157], v[98:113]
	v_add_f32_e32 v66, v72, v94
	v_add_f32_e32 v66, v73, v66
	v_add_f32_e32 v66, v74, v66
	v_add_f32_e32 v66, v75, v66
	v_cvt_pk_bf16_f32 v160, v70, v71
	v_cvt_pk_bf16_f32 v161, v72, v73
	ds_read_b64_tr_b16 v[70:71], v199 offset:27648
	ds_read_b64_tr_b16 v[72:73], v199 offset:28160
	s_waitcnt lgkmcnt(14)
	v_mfma_f32_32x32x16_bf16 v[114:129], v[134:137], v[146:149], v[114:129]
	v_add_f32_e32 v66, v76, v66
	v_add_f32_e32 v66, v77, v66
	v_add_f32_e32 v66, v78, v66
	v_add_f32_e32 v94, v79, v66
	v_cvt_pk_bf16_f32 v150, v74, v75
	v_cvt_pk_bf16_f32 v151, v76, v77
	ds_read_b64_tr_b16 v[66:67], v199 offset:31744
	ds_read_b64_tr_b16 v[68:69], v199 offset:32256
	v_mfma_f32_32x32x16_bf16 v[98:113], v[130:133], v[146:149], v[98:113]
	v_add_f32_e32 v74, v80, v94
	v_add_f32_e32 v76, v81, v74
	s_nop 0
	v_cvt_pk_bf16_f32 v152, v78, v79
	v_cvt_pk_bf16_f32 v153, v80, v81
	v_lshl_add_u64 v[74:75], v[204:205], 0, s[20:21]
	s_add_i32 s3, s12, s53
	s_mov_b32 s13, m0
	s_mov_b32 m0, s3
	s_nop 0
	global_load_lds_dwordx4 v[74:75], off
	s_mov_b32 m0, s13
	v_lshl_add_u64 v[74:75], v[202:203], 0, s[20:21]
	s_add_i32 s3, s55, s51
	s_mov_b32 s13, m0
	s_mov_b32 m0, s3
	s_nop 0
	global_load_lds_dwordx4 v[74:75], off
	s_mov_b32 m0, s13
	s_nop 0
	s_nop 0
	v_max_f32_e32 v74, v114, v115
	v_max3_f32 v75, v116, v117, v99
	v_max3_f32 v74, v74, v98, v100
	v_max3_f32 v74, v74, v101, v118
	v_max3_f32 v75, v75, v120, v121
	v_max3_f32 v74, v74, v119, v102
	v_max3_f32 v75, v75, v104, v105
	v_max3_f32 v74, v74, v103, v122
	v_max3_f32 v75, v75, v124, v125
	v_max3_f32 v74, v74, v123, v106
	v_max3_f32 v75, v75, v108, v109
	v_max3_f32 v74, v74, v107, v126
	v_max3_f32 v75, v75, v128, v129
	v_max3_f32 v74, v74, v127, v110
	v_max3_f32 v75, v75, v112, v113
	v_max3_f32 v74, v74, v111, v75
	v_mov_b32_e32 v75, v74
	s_nop 1
	v_permlane32_swap_b32_e32 v74, v75
	s_nop 0
	s_nop 0
	v_max_f32_e32 v74, v74, v75
	v_cmp_lt_f32_e32 vcc, s48, v74
	s_cmp_lg_u64 vcc, 0
	v_add_f32_e32 v222, v198, v76
	s_cselect_b64 s[38:39], -1, 0
	s_cbranch_vccnz .LBB0_1286

.LBB0_1281:
	s_add_i32 s3, s55, 0x2000
	s_cmpk_lg_i32 s55, 0x4000
	s_cselect_b32 s13, s3, 0
	v_add_u32_e32 v223, s12, v219
	ds_read_b64_tr_b16 v[142:143], v223 offset:24576
	ds_read_b64_tr_b16 v[144:145], v223 offset:25088
	s_waitcnt lgkmcnt(9)
	v_mfma_f32_32x32x16_bf16 v[82:97], v[74:77], v[170:173], v[50:65]
	v_add_f32_e32 v66, v114, v115
	v_add_f32_e32 v66, v116, v66
	v_add_f32_e32 v66, v117, v66
	v_add_f32_e32 v66, v118, v66
	v_add_f32_e32 v66, v119, v66
	v_cvt_pk_bf16_f32 v174, v114, v115
	v_cvt_pk_bf16_f32 v175, v116, v117
	ds_read_b64_tr_b16 v[138:139], v223 offset:28672
	ds_read_b64_tr_b16 v[140:141], v223 offset:29184
	v_add_f32_e32 v66, v120, v66
	v_add_f32_e32 v66, v121, v66
	v_add_f32_e32 v66, v122, v66
	v_add_f32_e32 v114, v123, v66
	s_waitcnt lgkmcnt(10)
	v_mfma_f32_32x32x16_bf16 v[66:81], v[130:133], v[170:173], v[50:65]
	v_cvt_pk_bf16_f32 v176, v118, v119
	v_cvt_pk_bf16_f32 v177, v120, v121
	ds_read_b64_tr_b16 v[134:135], v223 offset:25600
	ds_read_b64_tr_b16 v[136:137], v223 offset:26112
	s_waitcnt lgkmcnt(11)
	v_mfma_f32_32x32x16_bf16 v[82:97], v[198:201], v[162:165], v[82:97]
	v_add_f32_e32 v114, v124, v114
	v_add_f32_e32 v114, v125, v114
	v_add_f32_e32 v114, v126, v114
	v_add_f32_e32 v114, v127, v114
	v_cvt_pk_bf16_f32 v166, v122, v123
	v_cvt_pk_bf16_f32 v167, v124, v125
	ds_read_b64_tr_b16 v[130:131], v223 offset:29696
	ds_read_b64_tr_b16 v[132:133], v223 offset:30208
	s_waitcnt lgkmcnt(12)
	v_mfma_f32_32x32x16_bf16 v[66:81], v[190:193], v[162:165], v[66:81]
	v_add_f32_e32 v114, v128, v114
	v_add_f32_e32 v114, v129, v114
	v_add_f32_e32 v114, v98, v114
	v_add_f32_e32 v114, v99, v114
	v_cvt_pk_bf16_f32 v168, v126, v127
	v_cvt_pk_bf16_f32 v169, v128, v129
	ds_read_b64_tr_b16 v[122:123], v223 offset:26624
	ds_read_b64_tr_b16 v[124:125], v223 offset:27136
	s_waitcnt lgkmcnt(13)
	v_mfma_f32_32x32x16_bf16 v[82:97], v[194:197], v[154:157], v[82:97]
	v_add_f32_e32 v114, v100, v114
	v_add_f32_e32 v114, v101, v114
	v_add_f32_e32 v114, v102, v114
	v_add_f32_e32 v114, v103, v114
	v_cvt_pk_bf16_f32 v158, v98, v99
	v_cvt_pk_bf16_f32 v159, v100, v101
	ds_read_b64_tr_b16 v[118:119], v223 offset:30720
	ds_read_b64_tr_b16 v[120:121], v223 offset:31232
	s_waitcnt lgkmcnt(14)
	v_mfma_f32_32x32x16_bf16 v[66:81], v[182:185], v[154:157], v[66:81]
	v_add_f32_e32 v98, v104, v114
	v_add_f32_e32 v98, v105, v98
	v_add_f32_e32 v98, v106, v98
	v_add_f32_e32 v98, v107, v98
	v_cvt_pk_bf16_f32 v160, v102, v103
	v_cvt_pk_bf16_f32 v161, v104, v105
	ds_read_b64_tr_b16 v[114:115], v223 offset:27648
	ds_read_b64_tr_b16 v[116:117], v223 offset:28160
	s_waitcnt lgkmcnt(14)
	v_mfma_f32_32x32x16_bf16 v[82:97], v[186:189], v[146:149], v[82:97]
	v_add_f32_e32 v98, v108, v98
	v_add_f32_e32 v98, v109, v98
	v_add_f32_e32 v98, v110, v98
	v_add_f32_e32 v98, v111, v98
	v_cvt_pk_bf16_f32 v150, v106, v107
	v_cvt_pk_bf16_f32 v151, v108, v109
	ds_read_b64_tr_b16 v[102:103], v223 offset:31744
	ds_read_b64_tr_b16 v[104:105], v223 offset:32256
	v_mfma_f32_32x32x16_bf16 v[66:81], v[178:181], v[146:149], v[66:81]
	v_add_f32_e32 v98, v112, v98
	v_add_f32_e32 v98, v113, v98
	s_nop 0
	v_cvt_pk_bf16_f32 v152, v110, v111
	v_cvt_pk_bf16_f32 v153, v112, v113
	s_nop 0
	s_nop 0
	v_max_f32_e32 v99, v82, v83
	s_nop 3
	v_max3_f32 v100, v84, v85, v67
	v_max3_f32 v99, v99, v66, v68
	v_max3_f32 v99, v99, v69, v86
	v_max3_f32 v100, v100, v88, v89
	v_max3_f32 v99, v99, v87, v70
	v_max3_f32 v100, v100, v72, v73
	v_max3_f32 v99, v99, v71, v90
	v_max3_f32 v100, v100, v92, v93
	v_max3_f32 v99, v99, v91, v74
	v_max3_f32 v100, v100, v76, v77
	v_max3_f32 v99, v99, v75, v94
	v_max3_f32 v100, v100, v96, v97
	v_max3_f32 v99, v99, v95, v78
	v_max3_f32 v100, v100, v80, v81
	v_add_f32_e32 v198, v222, v98
	v_max3_f32 v98, v99, v79, v100
	v_mov_b32_e32 v99, v98
	s_nop 1
	v_permlane32_swap_b32_e32 v98, v99
	s_nop 0
	s_nop 0
	s_add_i32 s3, s55, s53
	s_mov_b32 s12, m0
	s_mov_b32 m0, s3
	s_nop 0
	global_load_lds_dwordx4 v[204:205], off
	s_mov_b32 m0, s12
	v_max_f32_e32 v98, v98, v99
	s_add_i32 s3, s13, s51
	s_mov_b32 s12, m0
	s_mov_b32 m0, s3
	s_nop 0
	global_load_lds_dwordx4 v[202:203], off
	s_mov_b32 m0, s12
	v_cmp_lt_f32_e32 vcc, s48, v98
	s_cmp_lg_u64 vcc, 0
	s_cselect_b64 s[38:39], -1, 0
	s_cbranch_vccnz .LBB0_1289

.LBB0_1292:
	ds_read_b64_tr_b16 v[194:195], v219 offset:24576
	ds_read_b64_tr_b16 v[196:197], v219 offset:25088
	s_waitcnt lgkmcnt(9)
	v_mfma_f32_32x32x16_bf16 v[114:129], v[98:101], v[170:173], v[50:65]
	v_add_f32_e32 v102, v82, v83
	v_add_f32_e32 v102, v84, v102
	v_add_f32_e32 v102, v85, v102
	v_add_f32_e32 v102, v86, v102
	v_add_f32_e32 v102, v87, v102
	v_cvt_pk_bf16_f32 v174, v82, v83
	v_cvt_pk_bf16_f32 v175, v84, v85
	ds_read_b64_tr_b16 v[190:191], v219 offset:28672
	ds_read_b64_tr_b16 v[192:193], v219 offset:29184
	v_add_f32_e32 v82, v88, v102
	s_waitcnt lgkmcnt(10)
	v_mfma_f32_32x32x16_bf16 v[98:113], v[186:189], v[170:173], v[50:65]
	v_add_f32_e32 v82, v89, v82
	v_add_f32_e32 v82, v90, v82
	v_add_f32_e32 v82, v91, v82
	v_cvt_pk_bf16_f32 v176, v86, v87
	v_cvt_pk_bf16_f32 v177, v88, v89
	ds_read_b64_tr_b16 v[186:187], v219 offset:25600
	ds_read_b64_tr_b16 v[188:189], v219 offset:26112
	s_waitcnt lgkmcnt(11)
	v_mfma_f32_32x32x16_bf16 v[114:129], v[182:185], v[162:165], v[114:129]
	v_add_f32_e32 v82, v92, v82
	v_add_f32_e32 v82, v93, v82
	v_add_f32_e32 v82, v94, v82
	v_add_f32_e32 v82, v95, v82
	v_cvt_pk_bf16_f32 v166, v90, v91
	v_cvt_pk_bf16_f32 v167, v92, v93
	ds_read_b64_tr_b16 v[90:91], v219 offset:29696
	ds_read_b64_tr_b16 v[92:93], v219 offset:30208
	s_waitcnt lgkmcnt(12)
	v_mfma_f32_32x32x16_bf16 v[98:113], v[178:181], v[162:165], v[98:113]
	v_add_f32_e32 v82, v96, v82
	v_add_f32_e32 v82, v97, v82
	v_add_f32_e32 v82, v66, v82
	v_add_f32_e32 v82, v67, v82
	v_cvt_pk_bf16_f32 v168, v94, v95
	v_cvt_pk_bf16_f32 v169, v96, v97
	ds_read_b64_tr_b16 v[86:87], v219 offset:26624
	ds_read_b64_tr_b16 v[88:89], v219 offset:27136
	s_waitcnt lgkmcnt(13)
	v_mfma_f32_32x32x16_bf16 v[114:129], v[142:145], v[154:157], v[114:129]
	v_add_f32_e32 v82, v68, v82
	v_add_f32_e32 v82, v69, v82
	v_add_f32_e32 v82, v70, v82
	v_add_f32_e32 v94, v71, v82
	v_cvt_pk_bf16_f32 v158, v66, v67
	v_cvt_pk_bf16_f32 v159, v68, v69
	ds_read_b64_tr_b16 v[82:83], v219 offset:30720
	ds_read_b64_tr_b16 v[84:85], v219 offset:31232
	s_waitcnt lgkmcnt(14)
	v_mfma_f32_32x32x16_bf16 v[98:113], v[138:141], v[154:157], v[98:113]
	v_add_f32_e32 v66, v72, v94
	v_add_f32_e32 v66, v73, v66
	v_add_f32_e32 v66, v74, v66
	v_add_f32_e32 v66, v75, v66
	v_cvt_pk_bf16_f32 v160, v70, v71
	v_cvt_pk_bf16_f32 v161, v72, v73
	ds_read_b64_tr_b16 v[70:71], v219 offset:27648
	ds_read_b64_tr_b16 v[72:73], v219 offset:28160
	s_waitcnt lgkmcnt(14)
	v_mfma_f32_32x32x16_bf16 v[114:129], v[134:137], v[146:149], v[114:129]
	v_add_f32_e32 v66, v76, v66
	v_add_f32_e32 v66, v77, v66
	v_add_f32_e32 v66, v78, v66
	v_add_f32_e32 v94, v79, v66
	v_cvt_pk_bf16_f32 v150, v74, v75
	v_cvt_pk_bf16_f32 v151, v76, v77
	ds_read_b64_tr_b16 v[66:67], v219 offset:31744
	ds_read_b64_tr_b16 v[68:69], v219 offset:32256
	v_mfma_f32_32x32x16_bf16 v[98:113], v[130:133], v[146:149], v[98:113]
	v_add_f32_e32 v74, v80, v94
	v_add_f32_e32 v74, v81, v74
	s_nop 0
	v_cvt_pk_bf16_f32 v152, v78, v79
	v_cvt_pk_bf16_f32 v153, v80, v81
	s_cmp_lg_u32 0, -1
	s_cselect_b32 s3, 0, 0
	v_add_f32_e32 v222, v198, v74
	v_lshl_add_u64 v[74:75], v[210:211], 0, s[22:23]
	s_add_i32 s53, s3, s50
	s_add_i32 s3, s53, 0x2000
	s_mov_b32 s12, m0
	s_mov_b32 m0, s3
	s_nop 0
	global_load_lds_dwordx4 v[74:75], off
	s_mov_b32 m0, s12
	v_lshl_add_u64 v[74:75], v[208:209], 0, s[24:25]
	s_add_i32 s53, s53, 0xa000
	s_mov_b32 s3, m0
	s_mov_b32 m0, s53
	s_nop 0
	global_load_lds_dwordx4 v[74:75], off
	s_mov_b32 m0, s3
	s_nop 0
	s_nop 0
	v_max_f32_e32 v74, v114, v115
	v_max3_f32 v75, v116, v117, v99
	v_max3_f32 v74, v74, v98, v100
	v_max3_f32 v74, v74, v101, v118
	v_max3_f32 v75, v75, v120, v121
	v_max3_f32 v74, v74, v119, v102
	v_max3_f32 v75, v75, v104, v105
	v_max3_f32 v74, v74, v103, v122
	v_max3_f32 v75, v75, v124, v125
	v_max3_f32 v74, v74, v123, v106
	v_max3_f32 v75, v75, v108, v109
	v_max3_f32 v74, v74, v107, v126
	v_max3_f32 v75, v75, v128, v129
	v_max3_f32 v74, v74, v127, v110
	v_max3_f32 v75, v75, v112, v113
	v_max3_f32 v74, v74, v111, v75
	v_mov_b32_e32 v75, v74
	s_nop 1
	v_permlane32_swap_b32_e32 v74, v75
	s_nop 0
	s_nop 0
	v_max_f32_e32 v74, v74, v75
	v_cmp_lt_f32_e32 vcc, s48, v74
	s_cmp_lg_u64 vcc, 0
	s_cselect_b64 s[38:39], -1, 0
	s_cbranch_vccnz .LBB0_1309

.LBB0_1295:
	ds_read_b64_tr_b16 v[182:183], v219 offset:32768
	ds_read_b64_tr_b16 v[184:185], v219 offset:33280
	s_waitcnt lgkmcnt(9)
	v_mfma_f32_32x32x16_bf16 v[130:145], v[74:77], v[170:173], v[50:65]
	v_add_f32_e32 v66, v114, v115
	v_add_f32_e32 v66, v116, v66
	v_add_f32_e32 v66, v117, v66
	v_add_f32_e32 v66, v118, v66
	v_add_f32_e32 v66, v119, v66
	v_cvt_pk_bf16_f32 v174, v114, v115
	v_cvt_pk_bf16_f32 v175, v116, v117
	ds_read_b64_tr_b16 v[178:179], v219 offset:36864
	ds_read_b64_tr_b16 v[180:181], v219 offset:37376
	v_add_f32_e32 v66, v120, v66
	v_add_f32_e32 v66, v121, v66
	v_add_f32_e32 v66, v122, v66
	v_add_f32_e32 v82, v123, v66
	s_waitcnt lgkmcnt(10)
	v_mfma_f32_32x32x16_bf16 v[66:81], v[198:201], v[170:173], v[50:65]
	v_cvt_pk_bf16_f32 v176, v118, v119
	v_cvt_pk_bf16_f32 v177, v120, v121
	ds_read_b64_tr_b16 v[118:119], v219 offset:33792
	ds_read_b64_tr_b16 v[120:121], v219 offset:34304
	s_waitcnt lgkmcnt(11)
	v_mfma_f32_32x32x16_bf16 v[130:145], v[202:205], v[162:165], v[130:145]
	v_add_f32_e32 v82, v124, v82
	v_add_f32_e32 v82, v125, v82
	v_add_f32_e32 v82, v126, v82
	v_add_f32_e32 v82, v127, v82
	v_cvt_pk_bf16_f32 v166, v122, v123
	v_cvt_pk_bf16_f32 v167, v124, v125
	ds_read_b64_tr_b16 v[114:115], v219 offset:37888
	ds_read_b64_tr_b16 v[116:117], v219 offset:38400
	s_waitcnt lgkmcnt(12)
	v_mfma_f32_32x32x16_bf16 v[66:81], v[94:97], v[162:165], v[66:81]
	v_add_f32_e32 v82, v128, v82
	v_add_f32_e32 v82, v129, v82
	v_add_f32_e32 v82, v98, v82
	v_add_f32_e32 v82, v99, v82
	v_cvt_pk_bf16_f32 v168, v126, v127
	v_cvt_pk_bf16_f32 v169, v128, v129
	ds_read_b64_tr_b16 v[94:95], v219 offset:34816
	ds_read_b64_tr_b16 v[96:97], v219 offset:35328
	s_waitcnt lgkmcnt(13)
	v_mfma_f32_32x32x16_bf16 v[130:145], v[90:93], v[154:157], v[130:145]
	v_add_f32_e32 v82, v100, v82
	v_add_f32_e32 v82, v101, v82
	v_add_f32_e32 v82, v102, v82
	v_add_f32_e32 v82, v103, v82
	v_cvt_pk_bf16_f32 v158, v98, v99
	v_cvt_pk_bf16_f32 v159, v100, v101
	ds_read_b64_tr_b16 v[90:91], v219 offset:38912
	ds_read_b64_tr_b16 v[92:93], v219 offset:39424
	s_waitcnt lgkmcnt(14)
	v_mfma_f32_32x32x16_bf16 v[66:81], v[190:193], v[154:157], v[66:81]
	v_add_f32_e32 v82, v104, v82
	v_add_f32_e32 v82, v105, v82
	v_add_f32_e32 v82, v106, v82
	v_add_f32_e32 v82, v107, v82
	v_cvt_pk_bf16_f32 v160, v102, v103
	v_cvt_pk_bf16_f32 v161, v104, v105
	ds_read_b64_tr_b16 v[86:87], v219 offset:35840
	ds_read_b64_tr_b16 v[88:89], v219 offset:36352
	s_waitcnt lgkmcnt(14)
	v_mfma_f32_32x32x16_bf16 v[130:145], v[194:197], v[146:149], v[130:145]
	v_add_f32_e32 v82, v108, v82
	v_add_f32_e32 v82, v109, v82
	v_add_f32_e32 v82, v110, v82
	v_add_f32_e32 v98, v111, v82
	v_cvt_pk_bf16_f32 v150, v106, v107
	v_cvt_pk_bf16_f32 v151, v108, v109
	ds_read_b64_tr_b16 v[82:83], v219 offset:39936
	ds_read_b64_tr_b16 v[84:85], v219 offset:40448
	v_mfma_f32_32x32x16_bf16 v[66:81], v[186:189], v[146:149], v[66:81]
	v_add_f32_e32 v98, v112, v98
	v_add_f32_e32 v98, v113, v98
	s_nop 0
	v_cvt_pk_bf16_f32 v152, v110, v111
	v_cvt_pk_bf16_f32 v153, v112, v113
	s_cmp_lg_u32 0, -1
	s_cselect_b32 s3, 0, 0
	v_add_f32_e32 v198, v222, v98
	v_lshl_add_u64 v[98:99], v[210:211], 0, s[26:27]
	s_add_i32 s3, s3, s50
	s_addk_i32 s3, 0x4000
	s_mov_b32 s12, m0
	s_mov_b32 m0, s3
	s_nop 0
	global_load_lds_dwordx4 v[98:99], off
	s_mov_b32 m0, s12
	v_lshl_add_u64 v[98:99], v[208:209], 0, s[28:29]
	s_mov_b32 s3, m0
	s_mov_b32 m0, s51
	s_nop 0
	global_load_lds_dwordx4 v[98:99], off
	s_mov_b32 m0, s3
	s_nop 0
	s_nop 0
	v_max_f32_e32 v98, v130, v131
	v_max3_f32 v99, v132, v133, v67
	v_max3_f32 v98, v98, v66, v68
	v_max3_f32 v98, v98, v69, v134
	v_max3_f32 v99, v99, v136, v137
	v_max3_f32 v98, v98, v135, v70
	v_max3_f32 v99, v99, v72, v73
	v_max3_f32 v98, v98, v71, v138
	v_max3_f32 v99, v99, v140, v141
	v_max3_f32 v98, v98, v139, v74
	v_max3_f32 v99, v99, v76, v77
	v_max3_f32 v98, v98, v75, v142
	v_max3_f32 v99, v99, v144, v145
	v_max3_f32 v98, v98, v143, v78
	v_max3_f32 v99, v99, v80, v81
	v_max3_f32 v98, v98, v79, v99
	v_mov_b32_e32 v99, v98
	s_nop 1
	v_permlane32_swap_b32_e32 v98, v99
	s_nop 0
	s_nop 0
	v_max_f32_e32 v98, v98, v99
	v_cmp_lt_f32_e32 vcc, s48, v98
	s_cmp_lg_u64 vcc, 0
	s_cselect_b64 s[38:39], -1, 0
	s_cbranch_vccnz .LBB0_1312

.LBB0_1298:
	ds_read_b64_tr_b16 v[178:179], v219 offset:40960
	ds_read_b64_tr_b16 v[180:181], v219 offset:41472
	s_waitcnt lgkmcnt(9)
	v_mfma_f32_32x32x16_bf16 v[98:113], v[126:129], v[170:173], v[50:65]
	v_add_f32_e32 v82, v130, v131
	v_add_f32_e32 v82, v132, v82
	v_add_f32_e32 v82, v133, v82
	v_add_f32_e32 v82, v134, v82
	v_add_f32_e32 v82, v135, v82
	v_cvt_pk_bf16_f32 v174, v130, v131
	v_cvt_pk_bf16_f32 v175, v132, v133
	ds_read_b64_tr_b16 v[130:131], v219 offset:45056
	ds_read_b64_tr_b16 v[132:133], v219 offset:45568
	v_add_f32_e32 v82, v136, v82
	v_add_f32_e32 v82, v137, v82
	v_add_f32_e32 v82, v138, v82
	v_add_f32_e32 v150, v139, v82
	s_waitcnt lgkmcnt(10)
	v_mfma_f32_32x32x16_bf16 v[82:97], v[122:125], v[170:173], v[50:65]
	v_cvt_pk_bf16_f32 v176, v134, v135
	v_cvt_pk_bf16_f32 v177, v136, v137
	ds_read_b64_tr_b16 v[126:127], v219 offset:41984
	ds_read_b64_tr_b16 v[128:129], v219 offset:42496
	s_waitcnt lgkmcnt(11)
	v_mfma_f32_32x32x16_bf16 v[98:113], v[194:197], v[162:165], v[98:113]
	v_add_f32_e32 v122, v140, v150
	v_add_f32_e32 v122, v141, v122
	v_add_f32_e32 v122, v142, v122
	v_add_f32_e32 v134, v143, v122
	v_cvt_pk_bf16_f32 v166, v138, v139
	v_cvt_pk_bf16_f32 v167, v140, v141
	ds_read_b64_tr_b16 v[122:123], v219 offset:46080
	ds_read_b64_tr_b16 v[124:125], v219 offset:46592
	s_waitcnt lgkmcnt(12)
	v_mfma_f32_32x32x16_bf16 v[82:97], v[118:121], v[162:165], v[82:97]
	v_add_f32_e32 v134, v144, v134
	v_add_f32_e32 v134, v145, v134
	v_add_f32_e32 v134, v66, v134
	v_add_f32_e32 v134, v67, v134
	v_cvt_pk_bf16_f32 v168, v142, v143
	v_cvt_pk_bf16_f32 v169, v144, v145
	ds_read_b64_tr_b16 v[118:119], v219 offset:43008
	ds_read_b64_tr_b16 v[120:121], v219 offset:43520
	s_waitcnt lgkmcnt(13)
	v_mfma_f32_32x32x16_bf16 v[98:113], v[114:117], v[154:157], v[98:113]
	v_add_f32_e32 v134, v68, v134
	v_add_f32_e32 v134, v69, v134
	v_add_f32_e32 v134, v70, v134
	v_add_f32_e32 v134, v71, v134
	v_cvt_pk_bf16_f32 v158, v66, v67
	v_cvt_pk_bf16_f32 v159, v68, v69
	ds_read_b64_tr_b16 v[114:115], v219 offset:47104
	ds_read_b64_tr_b16 v[116:117], v219 offset:47616
	s_waitcnt lgkmcnt(14)
	v_mfma_f32_32x32x16_bf16 v[82:97], v[186:189], v[154:157], v[82:97]
	v_add_f32_e32 v66, v72, v134
	v_add_f32_e32 v66, v73, v66
	v_add_f32_e32 v66, v74, v66
	v_add_f32_e32 v66, v75, v66
	v_cvt_pk_bf16_f32 v160, v70, v71
	v_cvt_pk_bf16_f32 v161, v72, v73
	ds_read_b64_tr_b16 v[70:71], v219 offset:44032
	ds_read_b64_tr_b16 v[72:73], v219 offset:44544
	s_waitcnt lgkmcnt(14)
	v_mfma_f32_32x32x16_bf16 v[98:113], v[190:193], v[146:149], v[98:113]
	v_add_f32_e32 v66, v76, v66
	v_add_f32_e32 v66, v77, v66
	v_add_f32_e32 v66, v78, v66
	v_add_f32_e32 v134, v79, v66
	v_cvt_pk_bf16_f32 v150, v74, v75
	v_cvt_pk_bf16_f32 v151, v76, v77
	ds_read_b64_tr_b16 v[66:67], v219 offset:48128
	ds_read_b64_tr_b16 v[68:69], v219 offset:48640
	v_mfma_f32_32x32x16_bf16 v[82:97], v[182:185], v[146:149], v[82:97]
	v_add_f32_e32 v74, v80, v134
	v_add_f32_e32 v74, v81, v74
	s_nop 0
	v_cvt_pk_bf16_f32 v152, v78, v79
	v_cvt_pk_bf16_f32 v153, v80, v81
	s_cmp_lg_u32 0, -1
	s_cselect_b32 s3, 0, 0
	v_add_f32_e32 v198, v198, v74
	v_lshl_add_u64 v[74:75], v[208:209], 0, s[22:23]
	s_add_i32 s3, s3, s50
	s_add_i32 s3, s3, 0x8000
	s_mov_b32 s12, m0
	s_mov_b32 m0, s3
	s_nop 0
	global_load_lds_dwordx4 v[74:75], off
	s_mov_b32 m0, s12
	s_nop 0
	s_nop 0
	v_max_f32_e32 v74, v98, v99
	v_max3_f32 v75, v100, v101, v83
	v_max3_f32 v74, v74, v82, v84
	v_max3_f32 v74, v74, v85, v102
	v_max3_f32 v75, v75, v104, v105
	v_max3_f32 v74, v74, v103, v86
	v_max3_f32 v75, v75, v88, v89
	v_max3_f32 v74, v74, v87, v106
	v_max3_f32 v75, v75, v108, v109
	v_max3_f32 v74, v74, v107, v90
	v_max3_f32 v75, v75, v92, v93
	v_max3_f32 v74, v74, v91, v110
	v_max3_f32 v75, v75, v112, v113
	v_max3_f32 v74, v74, v111, v94
	v_max3_f32 v75, v75, v96, v97
	v_max3_f32 v74, v74, v95, v75
	v_mov_b32_e32 v75, v74
	s_nop 1
	v_permlane32_swap_b32_e32 v74, v75
	s_nop 0
	s_nop 0
	v_max_f32_e32 v74, v74, v75
	v_cmp_lt_f32_e32 vcc, s48, v74
	s_cmp_lg_u64 vcc, 0
	s_cselect_b64 s[38:39], -1, 0
	s_cbranch_vccnz .LBB0_1315

.LBB0_1301:
	ds_read_b64_tr_b16 v[138:139], v219 offset:24576
	ds_read_b64_tr_b16 v[140:141], v219 offset:25088
	s_waitcnt lgkmcnt(9)
	v_mfma_f32_32x32x16_bf16 v[114:129], v[74:77], v[170:173], v[50:65]
	v_add_f32_e32 v66, v98, v99
	v_add_f32_e32 v66, v100, v66
	v_add_f32_e32 v66, v101, v66
	v_add_f32_e32 v66, v102, v66
	v_add_f32_e32 v66, v103, v66
	v_cvt_pk_bf16_f32 v174, v98, v99
	v_cvt_pk_bf16_f32 v175, v100, v101
	ds_read_b64_tr_b16 v[134:135], v219 offset:28672
	ds_read_b64_tr_b16 v[136:137], v219 offset:29184
	v_add_f32_e32 v66, v104, v66
	v_add_f32_e32 v66, v105, v66
	v_add_f32_e32 v66, v106, v66
	v_add_f32_e32 v98, v107, v66
	s_waitcnt lgkmcnt(10)
	v_mfma_f32_32x32x16_bf16 v[66:81], v[130:133], v[170:173], v[50:65]
	v_cvt_pk_bf16_f32 v176, v102, v103
	v_cvt_pk_bf16_f32 v177, v104, v105
	ds_read_b64_tr_b16 v[130:131], v219 offset:25600
	ds_read_b64_tr_b16 v[132:133], v219 offset:26112
	s_waitcnt lgkmcnt(11)
	v_mfma_f32_32x32x16_bf16 v[114:129], v[194:197], v[162:165], v[114:129]
	v_add_f32_e32 v98, v108, v98
	v_add_f32_e32 v98, v109, v98
	v_add_f32_e32 v98, v110, v98
	v_add_f32_e32 v98, v111, v98
	v_cvt_pk_bf16_f32 v166, v106, v107
	v_cvt_pk_bf16_f32 v167, v108, v109
	ds_read_b64_tr_b16 v[106:107], v219 offset:29696
	ds_read_b64_tr_b16 v[108:109], v219 offset:30208
	s_waitcnt lgkmcnt(12)
	v_mfma_f32_32x32x16_bf16 v[66:81], v[186:189], v[162:165], v[66:81]
	v_add_f32_e32 v98, v112, v98
	v_add_f32_e32 v98, v113, v98
	v_add_f32_e32 v98, v82, v98
	v_add_f32_e32 v98, v83, v98
	v_cvt_pk_bf16_f32 v168, v110, v111
	v_cvt_pk_bf16_f32 v169, v112, v113
	ds_read_b64_tr_b16 v[102:103], v219 offset:26624
	ds_read_b64_tr_b16 v[104:105], v219 offset:27136
	s_waitcnt lgkmcnt(13)
	v_mfma_f32_32x32x16_bf16 v[114:129], v[190:193], v[154:157], v[114:129]
	v_add_f32_e32 v98, v84, v98
	v_add_f32_e32 v98, v85, v98
	v_add_f32_e32 v98, v86, v98
	v_add_f32_e32 v110, v87, v98
	v_cvt_pk_bf16_f32 v158, v82, v83
	v_cvt_pk_bf16_f32 v159, v84, v85
	ds_read_b64_tr_b16 v[98:99], v219 offset:30720
	ds_read_b64_tr_b16 v[100:101], v219 offset:31232
	s_waitcnt lgkmcnt(14)
	v_mfma_f32_32x32x16_bf16 v[66:81], v[178:181], v[154:157], v[66:81]
	v_add_f32_e32 v82, v88, v110
	v_add_f32_e32 v82, v89, v82
	v_add_f32_e32 v82, v90, v82
	v_add_f32_e32 v82, v91, v82
	v_cvt_pk_bf16_f32 v160, v86, v87
	v_cvt_pk_bf16_f32 v161, v88, v89
	ds_read_b64_tr_b16 v[86:87], v219 offset:27648
	ds_read_b64_tr_b16 v[88:89], v219 offset:28160
	s_waitcnt lgkmcnt(14)
	v_mfma_f32_32x32x16_bf16 v[114:129], v[182:185], v[146:149], v[114:129]
	v_add_f32_e32 v82, v92, v82
	v_add_f32_e32 v82, v93, v82
	v_add_f32_e32 v82, v94, v82
	v_add_f32_e32 v110, v95, v82
	v_cvt_pk_bf16_f32 v150, v90, v91
	v_cvt_pk_bf16_f32 v151, v92, v93
	ds_read_b64_tr_b16 v[82:83], v219 offset:31744
	ds_read_b64_tr_b16 v[84:85], v219 offset:32256
	v_mfma_f32_32x32x16_bf16 v[66:81], v[142:145], v[146:149], v[66:81]
	v_add_f32_e32 v90, v96, v110
	v_add_f32_e32 v90, v97, v90
	s_nop 0
	v_cvt_pk_bf16_f32 v152, v94, v95
	v_cvt_pk_bf16_f32 v153, v96, v97
	s_nop 0
	v_add_f32_e32 v190, v198, v90
	v_lshl_add_u64 v[90:91], v[208:209], 0, s[26:27]
	s_mov_b32 s3, m0
	s_mov_b32 m0, s53
	s_nop 0
	global_load_lds_dwordx4 v[90:91], off
	s_mov_b32 m0, s3
	s_nop 0
	s_nop 0
	v_max_f32_e32 v90, v114, v115
	s_nop 0
	v_max3_f32 v91, v116, v117, v67
	v_max3_f32 v90, v90, v66, v68
	v_max3_f32 v90, v90, v69, v118
	v_max3_f32 v91, v91, v120, v121
	v_max3_f32 v90, v90, v119, v70
	v_max3_f32 v91, v91, v72, v73
	v_max3_f32 v90, v90, v71, v122
	v_max3_f32 v91, v91, v124, v125
	v_max3_f32 v90, v90, v123, v74
	v_max3_f32 v91, v91, v76, v77
	v_max3_f32 v90, v90, v75, v126
	v_max3_f32 v91, v91, v128, v129
	v_max3_f32 v90, v90, v127, v78
	v_max3_f32 v91, v91, v80, v81
	v_max3_f32 v90, v90, v79, v91
	v_mov_b32_e32 v91, v90
	s_nop 1
	v_permlane32_swap_b32_e32 v90, v91
	s_nop 0
	s_nop 0
	v_max_f32_e32 v90, v90, v91
	v_cmp_lt_f32_e32 vcc, s48, v90
	s_cmp_lg_u64 vcc, 0
	s_cselect_b64 s[38:39], -1, 0
	s_cbranch_vccnz .LBB0_1318

.LBB0_1304:
	ds_read_b64_tr_b16 v[138:139], v219 offset:32768
	ds_read_b64_tr_b16 v[140:141], v219 offset:33280
	v_add_f32_e32 v82, v114, v115
	v_add_f32_e32 v82, v116, v82
	v_add_f32_e32 v82, v117, v82
	v_add_f32_e32 v82, v118, v82
	v_add_f32_e32 v98, v119, v82
	s_waitcnt lgkmcnt(9)
	v_mfma_f32_32x32x16_bf16 v[82:97], v[134:137], v[170:173], v[50:65]
	v_cvt_pk_bf16_f32 v174, v114, v115
	v_cvt_pk_bf16_f32 v175, v116, v117
	ds_read_b64_tr_b16 v[134:135], v219 offset:36864
	ds_read_b64_tr_b16 v[136:137], v219 offset:37376
	s_waitcnt lgkmcnt(10)
	v_mfma_f32_32x32x16_bf16 v[50:65], v[182:185], v[170:173], v[50:65]
	v_add_f32_e32 v98, v120, v98
	v_add_f32_e32 v98, v121, v98
	v_add_f32_e32 v98, v122, v98
	v_add_f32_e32 v98, v123, v98
	v_cvt_pk_bf16_f32 v176, v118, v119
	v_cvt_pk_bf16_f32 v177, v120, v121
	ds_read_b64_tr_b16 v[130:131], v219 offset:33792
	ds_read_b64_tr_b16 v[132:133], v219 offset:34304
	s_waitcnt lgkmcnt(11)
	v_mfma_f32_32x32x16_bf16 v[82:97], v[186:189], v[162:165], v[82:97]
	v_add_f32_e32 v98, v124, v98
	v_add_f32_e32 v98, v125, v98
	v_add_f32_e32 v98, v126, v98
	v_add_f32_e32 v98, v127, v98
	v_cvt_pk_bf16_f32 v166, v122, v123
	v_cvt_pk_bf16_f32 v167, v124, v125
	ds_read_b64_tr_b16 v[118:119], v219 offset:37888
	ds_read_b64_tr_b16 v[120:121], v219 offset:38400
	s_waitcnt lgkmcnt(12)
	v_mfma_f32_32x32x16_bf16 v[50:65], v[110:113], v[162:165], v[50:65]
	v_add_f32_e32 v98, v128, v98
	v_add_f32_e32 v98, v129, v98
	v_add_f32_e32 v98, v66, v98
	v_add_f32_e32 v98, v67, v98
	v_cvt_pk_bf16_f32 v168, v126, v127
	v_cvt_pk_bf16_f32 v169, v128, v129
	ds_read_b64_tr_b16 v[114:115], v219 offset:34816
	ds_read_b64_tr_b16 v[116:117], v219 offset:35328
	s_waitcnt lgkmcnt(13)
	v_mfma_f32_32x32x16_bf16 v[82:97], v[178:181], v[154:157], v[82:97]
	v_add_f32_e32 v98, v68, v98
	v_add_f32_e32 v98, v69, v98
	v_add_f32_e32 v98, v70, v98
	v_add_f32_e32 v98, v71, v98
	v_cvt_pk_bf16_f32 v158, v66, v67
	v_cvt_pk_bf16_f32 v159, v68, v69
	ds_read_b64_tr_b16 v[110:111], v219 offset:38912
	ds_read_b64_tr_b16 v[112:113], v219 offset:39424
	s_waitcnt lgkmcnt(14)
	v_mfma_f32_32x32x16_bf16 v[50:65], v[106:109], v[154:157], v[50:65]
	v_add_f32_e32 v66, v72, v98
	v_add_f32_e32 v66, v73, v66
	v_add_f32_e32 v66, v74, v66
	v_add_f32_e32 v66, v75, v66
	v_cvt_pk_bf16_f32 v160, v70, v71
	v_cvt_pk_bf16_f32 v161, v72, v73
	ds_read_b64_tr_b16 v[106:107], v219 offset:35840
	ds_read_b64_tr_b16 v[108:109], v219 offset:36352
	s_waitcnt lgkmcnt(14)
	v_mfma_f32_32x32x16_bf16 v[82:97], v[142:145], v[146:149], v[82:97]
	v_add_f32_e32 v66, v76, v66
	v_add_f32_e32 v66, v77, v66
	v_add_f32_e32 v66, v78, v66
	v_add_f32_e32 v66, v79, v66
	v_cvt_pk_bf16_f32 v150, v74, v75
	v_cvt_pk_bf16_f32 v151, v76, v77
	ds_read_b64_tr_b16 v[98:99], v219 offset:39936
	ds_read_b64_tr_b16 v[100:101], v219 offset:40448
	v_mfma_f32_32x32x16_bf16 v[50:65], v[102:105], v[146:149], v[50:65]
	v_add_f32_e32 v66, v80, v66
	v_add_f32_e32 v66, v81, v66
	s_nop 0
	v_cvt_pk_bf16_f32 v152, v78, v79
	v_cvt_pk_bf16_f32 v153, v80, v81
	s_nop 0
	s_nop 0
	v_max_f32_e32 v67, v82, v83
	s_nop 3
	v_max3_f32 v68, v84, v85, v51
	v_max3_f32 v67, v67, v50, v52
	v_max3_f32 v67, v67, v53, v86
	v_max3_f32 v68, v68, v88, v89
	v_max3_f32 v67, v67, v87, v54
	v_max3_f32 v68, v68, v56, v57
	v_max3_f32 v67, v67, v55, v90
	v_max3_f32 v68, v68, v92, v93
	v_max3_f32 v67, v67, v91, v58
	v_max3_f32 v68, v68, v60, v61
	v_max3_f32 v67, v67, v59, v94
	v_max3_f32 v68, v68, v96, v97
	v_max3_f32 v67, v67, v95, v62
	v_max3_f32 v68, v68, v64, v65
	v_add_f32_e32 v102, v190, v66
	v_max3_f32 v66, v67, v63, v68
	v_mov_b32_e32 v67, v66
	s_nop 1
	v_permlane32_swap_b32_e32 v66, v67
	s_nop 0
	s_nop 0
	v_max_f32_e32 v66, v66, v67
	v_cmp_lt_f32_e32 vcc, s48, v66
	s_cmp_lg_u64 vcc, 0
	s_cselect_b64 s[38:39], -1, 0
	s_cbranch_vccnz .LBB0_1321
